# g1ogelu3 + unit-head fast path: pn/pm via shift/and when group height is 8 (skips the v_rcp integer division chain)
# speedup vs baseline: 1.0065x; 1.0037x over previous
;     __host__ __device__ bool next(int i, Unit& u) const {
;     ...
;         int wgid = (int)L; { const int q = nwg / NXCD, r = nwg % NXCD, xcd = wgid % NXCD, off = wgid / NXCD; wgid = (xcd < r ? xcd * (q + 1) : r * (q + 1) + (xcd - r) * q) + off; }
;         const int nig = WGM * nN, gid = wgid / nig, fm = gid * WGM, gsz = (nM - fm) < WGM ? (nM - fm) : WGM;
;         u.pm = fm + ((wgid % nig) % gsz); u.pn = (wgid % nig) / gsz; return true;
.LBB0_52:
	s_ashr_i32 s5, s10, 3
	s_add_i32 s5, s14, s5
	s_ashr_i32 s10, s5, 31
	s_lshr_b32 s10, s10, 26
	s_add_i32 s10, s5, s10
	s_ashr_i32 s12, s10, 6
	s_lshl_b32 s12, s12, 3
	s_sub_i32 s14, 0x100, s12
	s_min_i32 s14, s14, 8
	s_cmp_lg_u32 s14, 8
	s_cbranch_scc1 .Lslowdiv_fd4
	s_andn2_b32 s10, s10, 63
	s_sub_i32 s5, s5, s10
	s_ashr_i32 s56, s5, 3
	s_and_b32 s5, s5, 7
	s_add_i32 s58, s12, s5
	s_branch .LBB0_53
.Lslowdiv_fd4:
	s_abs_i32 s20, s14
	v_cvt_f32_u32_e32 v0, s20
	s_sub_i32 s26, 0, s20
	s_andn2_b32 s10, s10, 63
	s_sub_i32 s5, s5, s10
	v_rcp_iflag_f32_e32 v0, v0
	s_abs_i32 s10, s5
	s_xor_b32 s21, s5, s14
	s_ashr_i32 s21, s21, 31
	v_mul_f32_e32 v0, 0x4f7ffffe, v0
	v_cvt_u32_f32_e32 v0, v0
	s_nop 0
	v_readfirstlane_b32 s27, v0
	s_mul_i32 s26, s26, s27
	s_mul_hi_u32 s26, s27, s26
	s_add_i32 s27, s27, s26
	s_mul_hi_u32 s26, s10, s27
	s_mul_i32 s27, s26, s20
	s_sub_i32 s10, s10, s27
	s_add_i32 s36, s26, 1
	s_sub_i32 s27, s10, s20
	s_cmp_ge_u32 s10, s20
	s_cselect_b32 s26, s36, s26
	s_cselect_b32 s10, s27, s10
	s_add_i32 s27, s26, 1
	s_cmp_ge_u32 s10, s20
	s_cselect_b32 s10, s27, s26
	s_xor_b32 s10, s10, s21
	s_sub_i32 s56, s10, s21
	s_mul_i32 s10, s56, s14
	s_sub_i32 s5, s5, s10
	s_add_i32 s58, s12, s5

;     __host__ __device__ bool next(int i, Unit& u) const {
;     ...
;         int wgid = (int)L; { const int q = nwg / NXCD, r = nwg % NXCD, xcd = wgid % NXCD, off = wgid / NXCD; wgid = (xcd < r ? xcd * (q + 1) : r * (q + 1) + (xcd - r) * q) + off; }
;         const int nig = WGM * nN, gid = wgid / nig, fm = gid * WGM, gsz = (nM - fm) < WGM ? (nM - fm) : WGM;
;         u.pm = fm + ((wgid % nig) % gsz); u.pn = (wgid % nig) / gsz; return true;
.LBB0_106:
	s_ashr_i32 s5, s8, 3
	s_add_i32 s5, s12, s5
	s_ashr_i32 s8, s5, 31
	s_lshr_b32 s8, s8, 27
	s_add_i32 s8, s5, s8
	s_ashr_i32 s10, s8, 5
	s_lshl_b32 s10, s10, 3
	s_sub_i32 s12, 0x100, s10
	s_min_i32 s12, s12, 8
	s_cmp_lg_u32 s12, 8
	s_cbranch_scc1 .Lslowdiv_fd3
	s_andn2_b32 s8, s8, 31
	s_sub_i32 s5, s5, s8
	s_ashr_i32 s74, s5, 3
	s_and_b32 s5, s5, 7
	s_add_i32 s75, s10, s5
	s_branch .LBB0_107
.Lslowdiv_fd3:
	s_abs_i32 s14, s12
	v_cvt_f32_u32_e32 v0, s14
	s_sub_i32 s21, 0, s14
	s_andn2_b32 s8, s8, 31
	s_sub_i32 s5, s5, s8
	v_rcp_iflag_f32_e32 v0, v0
	s_abs_i32 s8, s5
	s_xor_b32 s20, s5, s12
	s_ashr_i32 s20, s20, 31
	v_mul_f32_e32 v0, 0x4f7ffffe, v0
	v_cvt_u32_f32_e32 v0, v0
	s_nop 0
	v_readfirstlane_b32 s26, v0
	s_mul_i32 s21, s21, s26
	s_mul_hi_u32 s21, s26, s21
	s_add_i32 s26, s26, s21
	s_mul_hi_u32 s21, s8, s26
	s_mul_i32 s26, s21, s14
	s_sub_i32 s8, s8, s26
	s_add_i32 s27, s21, 1
	s_sub_i32 s26, s8, s14
	s_cmp_ge_u32 s8, s14
	s_cselect_b32 s21, s27, s21
	s_cselect_b32 s8, s26, s8
	s_add_i32 s26, s21, 1
	s_cmp_ge_u32 s8, s14
	s_cselect_b32 s8, s26, s21
	s_xor_b32 s8, s8, s20
	s_sub_i32 s74, s8, s20
	s_mul_i32 s8, s74, s12
	s_sub_i32 s5, s5, s8
	s_add_i32 s75, s10, s5

;     __host__ __device__ bool next(int i, Unit& u) const {
;         const long L = (long)i * G + c; if (L >= nwg) return false;
;         int wgid = (int)L; { const int q = nwg / NXCD, r = nwg % NXCD, xcd = wgid % NXCD, off = wgid / NXCD; wgid = (xcd < r ? xcd * (q + 1) : r * (q + 1) + (xcd - r) * q) + off; }
;         const int nig = WGM * nN, gid = wgid / nig, fm = gid * WGM, gsz = (nM - fm) < WGM ? (nM - fm) : WGM;
;         u.pm = fm + ((wgid % nig) % gsz); u.pn = (wgid % nig) / gsz; return true;
.LBB0_149:
	s_add_i32 s71, s71, 1
	v_readlane_b32 s5, v252, 14
	s_mul_i32 s5, s71, s5
	s_mul_hi_u32 s8, s71, s9
	s_add_i32 s8, s8, s5
	s_mul_i32 s5, s71, s9
	s_add_u32 s26, s5, s76
	v_readlane_b32 s5, v254, 23
	s_addc_u32 s27, s8, s5
	v_mov_b64_e32 v[0:1], 0x1600
	v_cmp_lt_i64_e64 s[40:41], s[26:27], v[0:1]
	v_mov_b64_e32 v[0:1], 0x15ff
	v_cmp_gt_i64_e32 vcc, s[26:27], v[0:1]
	s_mov_b32 s8, s50
	s_cbranch_vccnz .LBB0_151
	s_ashr_i32 s5, s26, 31
	s_lshr_b32 s5, s5, 29
	s_add_i32 s5, s26, s5
	s_ashr_i32 s8, s5, 3
	s_and_b32 s5, s5, -8
	s_sub_i32 s5, s26, s5
	s_cmp_lt_i32 s5, 0
	s_movk_i32 s10, 0x2c1
	s_cselect_b32 s10, s10, 0x2c0
	s_mul_i32 s5, s5, s10
	s_add_i32 s5, s5, s8
	s_mul_hi_i32 s8, s5, 0x2e8ba2e9
	s_lshr_b32 s10, s8, 31
	s_ashr_i32 s8, s8, 5
	s_add_i32 s8, s8, s10
	s_lshl_b32 s10, s8, 3
	s_sub_i32 s12, 0x100, s10
	s_min_i32 s12, s12, 8
	s_cmp_lg_u32 s12, 8
	s_cbranch_scc1 .Lslowdiv_fd2
	s_mulk_i32 s8, 0xb0
	s_sub_i32 s5, s5, s8
	s_ashr_i32 s52, s5, 3
	s_and_b32 s5, s5, 7
	s_add_i32 s8, s10, s5
	s_branch .LBB0_151
.Lslowdiv_fd2:
	s_abs_i32 s14, s12
	v_cvt_f32_u32_e32 v0, s14
	s_sub_i32 s21, 0, s14
	s_mulk_i32 s8, 0xb0
	s_sub_i32 s5, s5, s8
	v_rcp_iflag_f32_e32 v0, v0
	s_abs_i32 s8, s5
	s_xor_b32 s20, s5, s12
	s_ashr_i32 s20, s20, 31
	v_mul_f32_e32 v0, 0x4f7ffffe, v0
	v_cvt_u32_f32_e32 v0, v0
	s_nop 0
	v_readfirstlane_b32 s26, v0
	s_mul_i32 s21, s21, s26
	s_mul_hi_u32 s21, s26, s21
	s_add_i32 s26, s26, s21
	s_mul_hi_u32 s21, s8, s26
	s_mul_i32 s26, s21, s14
	s_sub_i32 s8, s8, s26
	s_add_i32 s27, s21, 1
	s_sub_i32 s26, s8, s14
	s_cmp_ge_u32 s8, s14
	s_cselect_b32 s21, s27, s21
	s_cselect_b32 s8, s26, s8
	s_add_i32 s26, s21, 1
	s_cmp_ge_u32 s8, s14
	s_cselect_b32 s8, s26, s21
	s_xor_b32 s8, s8, s20
	s_sub_i32 s52, s8, s20
	s_mul_i32 s8, s52, s12
	s_sub_i32 s5, s5, s8
	s_add_i32 s8, s10, s5

;     __host__ __device__ bool next(int i, Unit& u) const {
;     ...
;         int wgid = (int)L; { const int q = nwg / NXCD, r = nwg % NXCD, xcd = wgid % NXCD, off = wgid / NXCD; wgid = (xcd < r ? xcd * (q + 1) : r * (q + 1) + (xcd - r) * q) + off; }
;         const int nig = WGM * nN, gid = wgid / nig, fm = gid * WGM, gsz = (nM - fm) < WGM ? (nM - fm) : WGM;
;         u.pm = fm + ((wgid % nig) % gsz); u.pn = (wgid % nig) / gsz; return true;
.LBB0_172:
	s_ashr_i32 s5, s8, 3
	s_add_i32 s5, s12, s5
	s_ashr_i32 s8, s5, 31
	s_lshr_b32 s8, s8, 27
	s_add_i32 s8, s5, s8
	s_ashr_i32 s10, s8, 5
	s_lshl_b32 s10, s10, 3
	s_sub_i32 s12, 0x100, s10
	s_min_i32 s12, s12, 8
	s_cmp_lg_u32 s12, 8
	s_cbranch_scc1 .Lslowdiv_fd1
	s_andn2_b32 s8, s8, 31
	s_sub_i32 s5, s5, s8
	s_ashr_i32 s52, s5, 3
	s_and_b32 s5, s5, 7
	s_add_i32 s54, s10, s5
	s_branch .LBB0_173
.Lslowdiv_fd1:
	s_abs_i32 s14, s12
	v_cvt_f32_u32_e32 v0, s14
	s_sub_i32 s21, 0, s14
	s_andn2_b32 s8, s8, 31
	s_sub_i32 s5, s5, s8
	v_rcp_iflag_f32_e32 v0, v0
	s_abs_i32 s8, s5
	s_xor_b32 s20, s5, s12
	s_ashr_i32 s20, s20, 31
	v_mul_f32_e32 v0, 0x4f7ffffe, v0
	v_cvt_u32_f32_e32 v0, v0
	s_nop 0
	v_readfirstlane_b32 s26, v0
	s_mul_i32 s21, s21, s26
	s_mul_hi_u32 s21, s26, s21
	s_add_i32 s26, s26, s21
	s_mul_hi_u32 s21, s8, s26
	s_mul_i32 s26, s21, s14
	s_sub_i32 s8, s8, s26
	s_add_i32 s27, s21, 1
	s_sub_i32 s26, s8, s14
	s_cmp_ge_u32 s8, s14
	s_cselect_b32 s21, s27, s21
	s_cselect_b32 s8, s26, s8
	s_add_i32 s26, s21, 1
	s_cmp_ge_u32 s8, s14
	s_cselect_b32 s8, s26, s21
	s_xor_b32 s8, s8, s20
	s_sub_i32 s52, s8, s20
	s_mul_i32 s8, s52, s12
	s_sub_i32 s5, s5, s8
	s_add_i32 s54, s10, s5

;     __host__ __device__ bool next(int i, Unit& u) const {
;     ...
;         int wgid = (int)L; { const int q = nwg / NXCD, r = nwg % NXCD, xcd = wgid % NXCD, off = wgid / NXCD; wgid = (xcd < r ? xcd * (q + 1) : r * (q + 1) + (xcd - r) * q) + off; }
;         const int nig = WGM * nN, gid = wgid / nig, fm = gid * WGM, gsz = (nM - fm) < WGM ? (nM - fm) : WGM;
;         u.pm = fm + ((wgid % nig) % gsz); u.pn = (wgid % nig) / gsz; return true;
.LBB0_412:
	s_ashr_i32 s4, s4, 3
	s_add_i32 s4, s10, s4
	s_ashr_i32 s8, s4, 31
	s_lshr_b32 s8, s8, 25
	s_add_i32 s8, s4, s8
	s_ashr_i32 s10, s8, 7
	s_lshl_b32 s10, s10, 3
	s_sub_i32 s12, 0x100, s10
	s_min_i32 s12, s12, 8
	s_cmp_lg_u32 s12, 8
	s_cbranch_scc1 .Lslowdiv_fd0
	s_and_b32 s8, s8, 0xffffff80
	s_sub_i32 s4, s4, s8
	s_ashr_i32 s46, s4, 3
	s_and_b32 s4, s4, 7
	s_add_i32 s48, s10, s4
	s_branch .LBB0_413
.Lslowdiv_fd0:
	s_abs_i32 s14, s12
	v_cvt_f32_u32_e32 v0, s14
	s_sub_i32 s27, 0, s14
	s_and_b32 s8, s8, 0xffffff80
	s_sub_i32 s4, s4, s8
	v_rcp_iflag_f32_e32 v0, v0
	s_abs_i32 s8, s4
	s_xor_b32 s26, s4, s12
	s_ashr_i32 s26, s26, 31
	v_mul_f32_e32 v0, 0x4f7ffffe, v0
	v_cvt_u32_f32_e32 v0, v0
	s_nop 0
	v_readfirstlane_b32 s36, v0
	s_mul_i32 s27, s27, s36
	s_mul_hi_u32 s27, s36, s27
	s_add_i32 s36, s36, s27
	s_mul_hi_u32 s27, s8, s36
	s_mul_i32 s36, s27, s14
	s_sub_i32 s8, s8, s36
	s_add_i32 s46, s27, 1
	s_sub_i32 s36, s8, s14
	s_cmp_ge_u32 s8, s14
	s_cselect_b32 s27, s46, s27
	s_cselect_b32 s8, s36, s8
	s_add_i32 s36, s27, 1
	s_cmp_ge_u32 s8, s14
	s_cselect_b32 s8, s36, s27
	s_xor_b32 s8, s8, s26
	s_sub_i32 s46, s8, s26
	s_mul_i32 s8, s46, s12
	s_sub_i32 s4, s4, s8
	s_add_i32 s48, s10, s4
